# attention QK phase: ninth K-fragment slot in a freed staging register quad, prefetch depth 8
# speedup vs baseline: 1.0075x; 1.0075x over previous
; __device__ __forceinline__ void attn_unit(LAS char* lds, const bf16_t* Qp, const bf16_t* KVp, const bf16_t* KRp, int ntiles, bf16_t* Yp, bool dry) {
;     ...
;         AT_QK(sb0, pa0, pa1);
;         AT_QK(sb0 + 1, pb0, pb1);
.Latt_noload:
	ds_read_b128 v[66:69], v0 offset:0
	ds_read_b128 v[70:73], v0 offset:6656
	ds_read_b128 v[74:77], v0 offset:32
	ds_read_b128 v[78:81], v0 offset:6688
	ds_read_b128 v[212:215], v0 offset:64
	ds_read_b128 v[240:243], v0 offset:6720
	ds_read_b128 v[244:247], v0 offset:96
	ds_read_b128 v[248:251], v0 offset:6752
	s_waitcnt lgkmcnt(7)
	v_mfma_f32_32x32x16_bf16 v[114:129], v[66:69], v[154:157], v[82:97]
	ds_read_b128 v[150:153], v0 offset:128
	s_waitcnt lgkmcnt(7)
	v_mfma_f32_32x32x16_bf16 v[98:113], v[70:73], v[154:157], v[82:97]
	ds_read_b128 v[66:69], v0 offset:6784
	s_waitcnt lgkmcnt(7)
	v_mfma_f32_32x32x16_bf16 v[114:129], v[74:77], v[158:161], v[114:129]
	ds_read_b128 v[70:73], v0 offset:160
	s_waitcnt lgkmcnt(7)
	v_mfma_f32_32x32x16_bf16 v[98:113], v[78:81], v[158:161], v[98:113]
	ds_read_b128 v[74:77], v0 offset:6816
	s_waitcnt lgkmcnt(7)
	v_mfma_f32_32x32x16_bf16 v[114:129], v[212:215], v[162:165], v[114:129]
	ds_read_b128 v[78:81], v0 offset:13312
	s_waitcnt lgkmcnt(7)
	v_mfma_f32_32x32x16_bf16 v[98:113], v[240:243], v[162:165], v[98:113]
	ds_read_b128 v[212:215], v0 offset:19968
	s_waitcnt lgkmcnt(7)
	v_mfma_f32_32x32x16_bf16 v[114:129], v[244:247], v[166:169], v[114:129]
	ds_read_b128 v[240:243], v0 offset:13344
	s_waitcnt lgkmcnt(7)
	v_mfma_f32_32x32x16_bf16 v[98:113], v[248:251], v[166:169], v[98:113]
	ds_read_b128 v[244:247], v0 offset:20000
	s_waitcnt lgkmcnt(7)
	v_mfma_f32_32x32x16_bf16 v[114:129], v[150:153], v[170:173], v[114:129]
	ds_read_b128 v[248:251], v0 offset:13376
	s_waitcnt lgkmcnt(7)
	v_mfma_f32_32x32x16_bf16 v[98:113], v[66:69], v[170:173], v[98:113]
	ds_read_b128 v[150:153], v0 offset:20032
	s_waitcnt lgkmcnt(7)
	v_mfma_f32_32x32x16_bf16 v[114:129], v[70:73], v[174:177], v[114:129]
	ds_read_b128 v[66:69], v0 offset:13408
	s_waitcnt lgkmcnt(7)
	v_mfma_f32_32x32x16_bf16 v[98:113], v[74:77], v[174:177], v[98:113]
	ds_read_b128 v[70:73], v0 offset:20064
	s_waitcnt lgkmcnt(7)
	v_mfma_f32_32x32x16_bf16 v[2:17], v[78:81], v[154:157], v[82:97]
	ds_read_b128 v[74:77], v0 offset:13440
	s_waitcnt lgkmcnt(7)
	v_mfma_f32_32x32x16_bf16 v[18:33], v[212:215], v[154:157], v[82:97]
	ds_read_b128 v[78:81], v0 offset:20096
	s_waitcnt lgkmcnt(7)
	v_mfma_f32_32x32x16_bf16 v[2:17], v[240:243], v[158:161], v[2:17]
	ds_read_b128 v[212:215], v0 offset:13472
	s_waitcnt lgkmcnt(7)
	v_mfma_f32_32x32x16_bf16 v[18:33], v[244:247], v[158:161], v[18:33]
	ds_read_b128 v[240:243], v0 offset:20128
	s_waitcnt lgkmcnt(7)
	v_mfma_f32_32x32x16_bf16 v[2:17], v[248:251], v[162:165], v[2:17]
	ds_read_b64_tr_b16 v[216:217], v185 offset:53248
	ds_read_b64_tr_b16 v[218:219], v185 offset:53760
	s_waitcnt lgkmcnt(8)
	v_mfma_f32_32x32x16_bf16 v[18:33], v[150:153], v[162:165], v[18:33]
	ds_read_b64_tr_b16 v[220:221], v185 offset:57344
	ds_read_b64_tr_b16 v[222:223], v185 offset:57856
	s_waitcnt lgkmcnt(9)
	v_mfma_f32_32x32x16_bf16 v[2:17], v[66:69], v[166:169], v[2:17]
	ds_read_b64_tr_b16 v[224:225], v185 offset:54272
	ds_read_b64_tr_b16 v[226:227], v185 offset:54784
	s_waitcnt lgkmcnt(10)
	v_mfma_f32_32x32x16_bf16 v[18:33], v[70:73], v[166:169], v[18:33]
	ds_read_b64_tr_b16 v[228:229], v185 offset:58368
	ds_read_b64_tr_b16 v[230:231], v185 offset:58880
	s_waitcnt lgkmcnt(11)
	v_mfma_f32_32x32x16_bf16 v[2:17], v[74:77], v[170:173], v[2:17]
	ds_read_b64_tr_b16 v[232:233], v185 offset:55296
	ds_read_b64_tr_b16 v[234:235], v185 offset:55808
	s_waitcnt lgkmcnt(12)
	v_mfma_f32_32x32x16_bf16 v[18:33], v[78:81], v[170:173], v[18:33]
	ds_read_b64_tr_b16 v[236:237], v185 offset:59392
	ds_read_b64_tr_b16 v[238:239], v185 offset:59904
	s_waitcnt lgkmcnt(13)
	v_mfma_f32_32x32x16_bf16 v[2:17], v[212:215], v[174:177], v[2:17]
	s_waitcnt lgkmcnt(12)
	v_mfma_f32_32x32x16_bf16 v[18:33], v[240:243], v[174:177], v[18:33]
	s_cmp_lg_u32 s35, 34
	s_cbranch_scc1 .Latt_nogate
	s_mul_i32 s14, s28, 0x1c00
	s_mul_hi_u32 s15, s25, 0x1c00
	s_add_i32 s15, s15, s14
	s_mul_i32 s14, s25, 0x1c00
	s_add_u32 s14, s88, s14
	s_addc_u32 s15, s89, s15
	s_lshl_b32 s2, s34, 1
	s_add_u32 s14, s14, s2
	s_addc_u32 s15, s15, 0
	v_lshlrev_b32_e32 v146, 1, v196
	v_mov_b32_e32 v147, 0
	s_mov_b64 s[2:3], 0x1000
	v_lshl_add_u64 v[146:147], s[14:15], 0, v[146:147]
	v_lshrrev_b32_e32 v148, 3, v191
	v_lshl_add_u64 v[146:147], v[146:147], 0, s[2:3]
	v_or_b32_e32 v148, s24, v148
	v_mad_i64_i32 v[150:151], s[16:17], v148, s13, v[146:147]
	v_or_b32_e32 v149, 8, v148
	global_load_dwordx4 v[130:133], v[150:151], off
	v_mad_i64_i32 v[152:153], s[16:17], v149, s13, v[146:147]
	v_or_b32_e32 v149, 16, v148
	global_load_dwordx4 v[134:137], v[152:153], off
	v_mad_i64_i32 v[150:151], s[16:17], v149, s13, v[146:147]
	v_or_b32_e32 v149, 24, v148
	global_load_dwordx4 v[138:141], v[150:151], off
	v_mad_i64_i32 v[152:153], s[16:17], v149, s13, v[146:147]
	s_nop 0
	global_load_dwordx4 v[142:145], v[152:153], off
